# residual epilogues: both row-sum exchange stages (lane^16, lane^32) by permlane swaps, no LDS round trips (128 sites), on fgate v3 + barrier edits
# baseline (speedup 1.0000x reference)
; __device__ __forceinline__ void store16_wt(void* p, wt_u32x4 v) { asm volatile("global_store_dwordx4 %0, %1, off sc1\n\ts_nop 1" :: "v"(p), "v"(v) : "memory"); }
; __device__ __forceinline__ float lane_get(float v, int src_lane) { return __builtin_bit_cast(float, __builtin_amdgcn_ds_bpermute(src_lane << 2, __builtin_bit_cast(int, v))); }
; __device__ __forceinline__ unsigned cvt_pk_bf16(float lo, float hi) { unsigned r; asm volatile("v_cvt_pk_bf16_f32 %0, %1, %2" : "=v"(r) : "v"(lo), "v"(hi)); return r; }
;     __device__ __forceinline__ void operator()(const f32x4 (&acc)[2][2][4][2], const Unit& u, int wr, int wc, int fr, int fq, int ui) const {
;     ...
;         const int row0 = u.pm * BM + wr * 64 + fr, col0 = u.pn * BM + wc * 32 + 8 * fq, lane = fq * 16 + fr;
; #pragma unroll
;         for (int ai = 0; ai < 2; ++ai)
; #pragma unroll
;             for (int m = 0; m < 4; ++m) { const int row = row0 + ai * HALF + m * 16; bf16_t* rowb = XB + (size_t)row * ldc + col0; float ss = 0.f;
; #pragma unroll
;                 for (int bj = 0; bj < 2; ++bj) { const f32x4 x0 = acc[ai][bj][m][0], x1 = acc[ai][bj][m][1];
;                     ss += ((x0[0] * x0[0] + x0[1] * x0[1]) + (x0[2] * x0[2] + x0[3] * x0[3])) + ((x1[0] * x1[0] + x1[1] * x1[1]) + (x1[2] * x1[2] + x1[3] * x1[3]));
;                     u32x4 w; w.x = cvt_pk_bf16(x0[0], x0[1]); w.y = cvt_pk_bf16(x0[2], x0[3]); w.z = cvt_pk_bf16(x1[0], x1[1]); w.w = cvt_pk_bf16(x1[2], x1[3]); store16_wt(rowb + bj * HALF, w); }
;                 ss += lane_get(ss, lane ^ 16); ss += lane_get(ss, lane ^ 32);
;                 if (fq == 0) __hip_atomic_store((unsigned*)stats + (size_t)row * 16 + u.pn * 4 + wc, __float_as_uint(ss), __ATOMIC_RELAXED, __HIP_MEMORY_SCOPE_AGENT); }
.LBB0_300:
	v_lshl_add_u32 v146, s70, 8, v148
	v_lshl_or_b32 v144, s69, 8, v152
	v_ashrrev_i32_e32 v145, 31, v144
	v_ashrrev_i32_e32 v147, 31, v146
	v_mul_f32_e32 v156, v113, v113
	v_lshl_add_u64 v[144:145], v[144:145], 1, s[10:11]
	v_lshlrev_b64 v[154:155], 11, v[146:147]
	v_fmac_f32_e32 v156, v112, v112
	v_mul_f32_e32 v157, v115, v115
	v_cvt_pk_bf16_f32 v112, v112, v113
	v_cvt_pk_bf16_f32 v113, v114, v115
	v_lshl_add_u64 v[154:155], v[144:145], 0, v[154:155]
	v_fmac_f32_e32 v157, v114, v114
	v_cvt_pk_bf16_f32 v114, v120, v121
	v_cvt_pk_bf16_f32 v115, v122, v123
	v_add_f32_e32 v156, v156, v157
	global_store_dwordx4 v[154:155], v[112:115], off sc1
	s_nop 1
	v_mul_f32_e32 v112, v117, v117
	v_mul_f32_e32 v113, v119, v119
	v_fmac_f32_e32 v112, v116, v116
	v_fmac_f32_e32 v113, v118, v118
	v_mul_f32_e32 v157, v121, v121
	v_mul_f32_e32 v158, v123, v123
	v_add_f32_e32 v112, v112, v113
	v_mul_f32_e32 v113, v125, v125
	v_mul_f32_e32 v114, v127, v127
	v_fmac_f32_e32 v157, v120, v120
	v_fmac_f32_e32 v158, v122, v122
	v_fmac_f32_e32 v113, v124, v124
	v_fmac_f32_e32 v114, v126, v126
	v_add_f32_e32 v157, v157, v158
	v_add_f32_e32 v113, v113, v114
	v_add_f32_e32 v156, v156, v157
	v_add_f32_e32 v112, v112, v113
	v_add_f32_e32 v112, v156, v112
	v_mov_b32_e32 v113, v112
	s_nop 1
	v_permlane16_swap_b32_e32 v113, v112
	s_lshl_b32 s30, s69, 2
	s_ashr_i32 s31, s30, 31
	s_lshl_b64 s[30:31], s[30:31], 2
	v_cvt_pk_bf16_f32 v114, v116, v117
	s_waitcnt lgkmcnt(0)
	v_add_f32_e32 v112, v112, v113
	v_mov_b32_e32 v113, v112
	s_nop 1
	v_permlane32_swap_b32_e32 v113, v112
	v_cvt_pk_bf16_f32 v115, v118, v119
	v_cvt_pk_bf16_f32 v116, v124, v125
	v_cvt_pk_bf16_f32 v117, v126, v127
	v_lshl_add_u64 v[118:119], v[154:155], 0, s[26:27]
	global_store_dwordx4 v[118:119], v[114:117], off sc1
	s_nop 1
	s_add_u32 s30, s62, s30
	s_addc_u32 s31, s63, s31
	s_and_saveexec_b64 s[34:35], s[2:3]
	s_cbranch_execz .LBB0_302
	v_lshlrev_b64 v[114:115], 6, v[146:147]
	v_lshl_add_u64 v[114:115], s[30:31], 0, v[114:115]
	s_waitcnt lgkmcnt(0)
	v_add_f32_e32 v112, v112, v113
	global_store_dword v[114:115], v112, off sc1
.LBB0_302:
	s_or_b64 exec, exec, s[34:35]
	v_or_b32_e32 v112, 16, v146
	s_waitcnt lgkmcnt(0)
	v_ashrrev_i32_e32 v113, 31, v112
	v_mul_f32_e32 v116, v97, v97
	v_lshlrev_b64 v[114:115], 11, v[112:113]
	v_fmac_f32_e32 v116, v96, v96
	v_mul_f32_e32 v117, v99, v99
	v_cvt_pk_bf16_f32 v96, v96, v97
	v_cvt_pk_bf16_f32 v97, v98, v99
	v_lshl_add_u64 v[114:115], v[144:145], 0, v[114:115]
	v_fmac_f32_e32 v117, v98, v98
	v_cvt_pk_bf16_f32 v98, v104, v105
	v_cvt_pk_bf16_f32 v99, v106, v107
	v_add_f32_e32 v116, v116, v117
	global_store_dwordx4 v[114:115], v[96:99], off sc1
	s_nop 1
	v_mul_f32_e32 v96, v101, v101
	v_mul_f32_e32 v97, v103, v103
	v_fmac_f32_e32 v96, v100, v100
	v_fmac_f32_e32 v97, v102, v102
	v_mul_f32_e32 v117, v105, v105
	v_mul_f32_e32 v118, v107, v107
	v_add_f32_e32 v96, v96, v97
	v_mul_f32_e32 v97, v109, v109
	v_mul_f32_e32 v98, v111, v111
	v_fmac_f32_e32 v117, v104, v104
	v_fmac_f32_e32 v118, v106, v106
	v_fmac_f32_e32 v97, v108, v108
	v_fmac_f32_e32 v98, v110, v110
	v_add_f32_e32 v117, v117, v118
	v_add_f32_e32 v97, v97, v98
	v_add_f32_e32 v116, v116, v117
	v_add_f32_e32 v96, v96, v97
	v_add_f32_e32 v96, v116, v96
	v_mov_b32_e32 v97, v96
	s_nop 1
	v_permlane16_swap_b32_e32 v97, v96
	v_cvt_pk_bf16_f32 v98, v100, v101
	v_cvt_pk_bf16_f32 v99, v102, v103
	v_cvt_pk_bf16_f32 v100, v108, v109
	v_cvt_pk_bf16_f32 v101, v110, v111
	s_waitcnt lgkmcnt(0)
	v_add_f32_e32 v96, v96, v97
	v_mov_b32_e32 v97, v96
	s_nop 1
	v_permlane32_swap_b32_e32 v97, v96
	v_lshl_add_u64 v[102:103], v[114:115], 0, s[26:27]
	global_store_dwordx4 v[102:103], v[98:101], off sc1
	s_nop 1
	s_and_saveexec_b64 s[34:35], s[2:3]
	s_cbranch_execz .LBB0_304
	v_lshlrev_b64 v[98:99], 6, v[112:113]
	v_lshl_add_u64 v[98:99], s[30:31], 0, v[98:99]
	s_waitcnt lgkmcnt(0)
	v_add_f32_e32 v96, v96, v97
	global_store_dword v[98:99], v96, off sc1
.LBB0_304:
	s_or_b64 exec, exec, s[34:35]
	v_or_b32_e32 v96, 32, v146
	s_waitcnt lgkmcnt(0)
	v_ashrrev_i32_e32 v97, 31, v96
	v_mul_f32_e32 v100, v81, v81
	v_lshlrev_b64 v[98:99], 11, v[96:97]
	v_fmac_f32_e32 v100, v80, v80
	v_mul_f32_e32 v101, v83, v83
	v_cvt_pk_bf16_f32 v80, v80, v81
	v_cvt_pk_bf16_f32 v81, v82, v83
	v_lshl_add_u64 v[98:99], v[144:145], 0, v[98:99]
	v_fmac_f32_e32 v101, v82, v82
	v_cvt_pk_bf16_f32 v82, v88, v89
	v_cvt_pk_bf16_f32 v83, v90, v91
	v_add_f32_e32 v100, v100, v101
	global_store_dwordx4 v[98:99], v[80:83], off sc1
	s_nop 1
	v_mul_f32_e32 v80, v85, v85
	v_mul_f32_e32 v81, v87, v87
	v_fmac_f32_e32 v80, v84, v84
	v_fmac_f32_e32 v81, v86, v86
	v_mul_f32_e32 v101, v89, v89
	v_mul_f32_e32 v102, v91, v91
	v_add_f32_e32 v80, v80, v81
	v_mul_f32_e32 v81, v93, v93
	v_mul_f32_e32 v82, v95, v95
	v_fmac_f32_e32 v101, v88, v88
	v_fmac_f32_e32 v102, v90, v90
	v_fmac_f32_e32 v81, v92, v92
	v_fmac_f32_e32 v82, v94, v94
	v_add_f32_e32 v101, v101, v102
	v_add_f32_e32 v81, v81, v82
	v_add_f32_e32 v100, v100, v101
	v_add_f32_e32 v80, v80, v81
	v_add_f32_e32 v80, v100, v80
	v_mov_b32_e32 v81, v80
	s_nop 1
	v_permlane16_swap_b32_e32 v81, v80
	v_cvt_pk_bf16_f32 v82, v84, v85
	v_cvt_pk_bf16_f32 v83, v86, v87
	v_cvt_pk_bf16_f32 v84, v92, v93
	v_cvt_pk_bf16_f32 v85, v94, v95
	s_waitcnt lgkmcnt(0)
	v_add_f32_e32 v80, v80, v81
	v_mov_b32_e32 v81, v80
	s_nop 1
	v_permlane32_swap_b32_e32 v81, v80
	v_lshl_add_u64 v[86:87], v[98:99], 0, s[26:27]
	global_store_dwordx4 v[86:87], v[82:85], off sc1
	s_nop 1
	s_and_saveexec_b64 s[34:35], s[2:3]
	s_cbranch_execz .LBB0_306
	v_lshlrev_b64 v[82:83], 6, v[96:97]
	v_lshl_add_u64 v[82:83], s[30:31], 0, v[82:83]
	s_waitcnt lgkmcnt(0)
	v_add_f32_e32 v80, v80, v81
	global_store_dword v[82:83], v80, off sc1
; __device__ __forceinline__ void store16_wt(void* p, wt_u32x4 v) { asm volatile("global_store_dwordx4 %0, %1, off sc1\n\ts_nop 1" :: "v"(p), "v"(v) : "memory"); }
; __device__ __forceinline__ float lane_get(float v, int src_lane) { return __builtin_bit_cast(float, __builtin_amdgcn_ds_bpermute(src_lane << 2, __builtin_bit_cast(int, v))); }
; __device__ __forceinline__ unsigned cvt_pk_bf16(float lo, float hi) { unsigned r; asm volatile("v_cvt_pk_bf16_f32 %0, %1, %2" : "=v"(r) : "v"(lo), "v"(hi)); return r; }
;     __device__ __forceinline__ void operator()(const f32x4 (&acc)[2][2][4][2], const Unit& u, int wr, int wc, int fr, int fq, int ui) const {
;     ...
;         const int row0 = u.pm * BM + wr * 64 + fr, col0 = u.pn * BM + wc * 32 + 8 * fq, lane = fq * 16 + fr;
; #pragma unroll
;         for (int ai = 0; ai < 2; ++ai)
; #pragma unroll
;             for (int m = 0; m < 4; ++m) { const int row = row0 + ai * HALF + m * 16; bf16_t* rowb = XB + (size_t)row * ldc + col0; float ss = 0.f;
; #pragma unroll
;                 for (int bj = 0; bj < 2; ++bj) { const f32x4 x0 = acc[ai][bj][m][0], x1 = acc[ai][bj][m][1];
;                     ss += ((x0[0] * x0[0] + x0[1] * x0[1]) + (x0[2] * x0[2] + x0[3] * x0[3])) + ((x1[0] * x1[0] + x1[1] * x1[1]) + (x1[2] * x1[2] + x1[3] * x1[3]));
;                     u32x4 w; w.x = cvt_pk_bf16(x0[0], x0[1]); w.y = cvt_pk_bf16(x0[2], x0[3]); w.z = cvt_pk_bf16(x1[0], x1[1]); w.w = cvt_pk_bf16(x1[2], x1[3]); store16_wt(rowb + bj * HALF, w); }
;                 ss += lane_get(ss, lane ^ 16); ss += lane_get(ss, lane ^ 32);
;                 if (fq == 0) __hip_atomic_store((unsigned*)stats + (size_t)row * 16 + u.pn * 4 + wc, __float_as_uint(ss), __ATOMIC_RELAXED, __HIP_MEMORY_SCOPE_AGENT); }
.LBB0_306:
	s_or_b64 exec, exec, s[34:35]
	v_or_b32_e32 v80, 48, v146
	s_waitcnt lgkmcnt(0)
	v_ashrrev_i32_e32 v81, 31, v80
	v_mul_f32_e32 v84, v65, v65
	v_lshlrev_b64 v[82:83], 11, v[80:81]
	v_fmac_f32_e32 v84, v64, v64
	v_mul_f32_e32 v85, v67, v67
	v_cvt_pk_bf16_f32 v64, v64, v65
	v_cvt_pk_bf16_f32 v65, v66, v67
	v_lshl_add_u64 v[82:83], v[144:145], 0, v[82:83]
	v_fmac_f32_e32 v85, v66, v66
	v_cvt_pk_bf16_f32 v66, v72, v73
	v_cvt_pk_bf16_f32 v67, v74, v75
	v_add_f32_e32 v84, v84, v85
	global_store_dwordx4 v[82:83], v[64:67], off sc1
	s_nop 1
	v_mul_f32_e32 v64, v69, v69
	v_mul_f32_e32 v65, v71, v71
	v_fmac_f32_e32 v64, v68, v68
	v_fmac_f32_e32 v65, v70, v70
	v_mul_f32_e32 v85, v73, v73
	v_mul_f32_e32 v86, v75, v75
	v_add_f32_e32 v64, v64, v65
	v_mul_f32_e32 v65, v77, v77
	v_mul_f32_e32 v66, v79, v79
	v_fmac_f32_e32 v85, v72, v72
	v_fmac_f32_e32 v86, v74, v74
	v_fmac_f32_e32 v65, v76, v76
	v_fmac_f32_e32 v66, v78, v78
	v_add_f32_e32 v85, v85, v86
	v_add_f32_e32 v65, v65, v66
	v_add_f32_e32 v84, v84, v85
	v_add_f32_e32 v64, v64, v65
	v_add_f32_e32 v64, v84, v64
	v_mov_b32_e32 v65, v64
	s_nop 1
	v_permlane16_swap_b32_e32 v65, v64
	v_cvt_pk_bf16_f32 v66, v68, v69
	v_cvt_pk_bf16_f32 v67, v70, v71
	v_cvt_pk_bf16_f32 v68, v76, v77
	v_cvt_pk_bf16_f32 v69, v78, v79
	s_waitcnt lgkmcnt(0)
	v_add_f32_e32 v64, v64, v65
	v_mov_b32_e32 v65, v64
	s_nop 1
	v_permlane32_swap_b32_e32 v65, v64
	v_lshl_add_u64 v[70:71], v[82:83], 0, s[26:27]
	global_store_dwordx4 v[70:71], v[66:69], off sc1
	s_nop 1
	s_and_saveexec_b64 s[34:35], s[2:3]
	s_cbranch_execz .LBB0_308
	v_lshlrev_b64 v[66:67], 6, v[80:81]
	v_lshl_add_u64 v[66:67], s[30:31], 0, v[66:67]
	s_waitcnt lgkmcnt(0)
	v_add_f32_e32 v64, v64, v65
	global_store_dword v[66:67], v64, off sc1
.LBB0_308:
	s_or_b64 exec, exec, s[34:35]
	v_add_u32_e32 v64, 0x80, v146
	s_waitcnt lgkmcnt(0)
	v_ashrrev_i32_e32 v65, 31, v64
	v_mul_f32_e32 v68, v49, v49
	v_lshlrev_b64 v[66:67], 11, v[64:65]
	v_fmac_f32_e32 v68, v48, v48
	v_mul_f32_e32 v69, v51, v51
	v_cvt_pk_bf16_f32 v48, v48, v49
	v_cvt_pk_bf16_f32 v49, v50, v51
	v_lshl_add_u64 v[66:67], v[144:145], 0, v[66:67]
	v_fmac_f32_e32 v69, v50, v50
	v_cvt_pk_bf16_f32 v50, v56, v57
	v_cvt_pk_bf16_f32 v51, v58, v59
	v_add_f32_e32 v68, v68, v69
	global_store_dwordx4 v[66:67], v[48:51], off sc1
	s_nop 1
	v_mul_f32_e32 v48, v53, v53
	v_mul_f32_e32 v49, v55, v55
	v_fmac_f32_e32 v48, v52, v52
	v_fmac_f32_e32 v49, v54, v54
	v_mul_f32_e32 v69, v57, v57
	v_mul_f32_e32 v70, v59, v59
	v_add_f32_e32 v48, v48, v49
	v_mul_f32_e32 v49, v61, v61
	v_mul_f32_e32 v50, v63, v63
	v_fmac_f32_e32 v69, v56, v56
	v_fmac_f32_e32 v70, v58, v58
	v_fmac_f32_e32 v49, v60, v60
	v_fmac_f32_e32 v50, v62, v62
	v_add_f32_e32 v69, v69, v70
	v_add_f32_e32 v49, v49, v50
	v_add_f32_e32 v68, v68, v69
	v_add_f32_e32 v48, v48, v49
	v_add_f32_e32 v48, v68, v48
	v_mov_b32_e32 v49, v48
	s_nop 1
	v_permlane16_swap_b32_e32 v49, v48
	v_cvt_pk_bf16_f32 v50, v52, v53
	v_cvt_pk_bf16_f32 v51, v54, v55
	v_cvt_pk_bf16_f32 v52, v60, v61
	v_cvt_pk_bf16_f32 v53, v62, v63
	s_waitcnt lgkmcnt(0)
	v_add_f32_e32 v48, v48, v49
	v_mov_b32_e32 v49, v48
	s_nop 1
	v_permlane32_swap_b32_e32 v49, v48
	v_lshl_add_u64 v[54:55], v[66:67], 0, s[26:27]
	global_store_dwordx4 v[54:55], v[50:53], off sc1
	s_nop 1
	s_and_saveexec_b64 s[34:35], s[2:3]
	s_cbranch_execz .LBB0_310
	v_lshlrev_b64 v[50:51], 6, v[64:65]
	v_lshl_add_u64 v[50:51], s[30:31], 0, v[50:51]
	s_waitcnt lgkmcnt(0)
	v_add_f32_e32 v48, v48, v49
	global_store_dword v[50:51], v48, off sc1
; __device__ __forceinline__ void store16_wt(void* p, wt_u32x4 v) { asm volatile("global_store_dwordx4 %0, %1, off sc1\n\ts_nop 1" :: "v"(p), "v"(v) : "memory"); }
; __device__ __forceinline__ float lane_get(float v, int src_lane) { return __builtin_bit_cast(float, __builtin_amdgcn_ds_bpermute(src_lane << 2, __builtin_bit_cast(int, v))); }
; __device__ __forceinline__ unsigned cvt_pk_bf16(float lo, float hi) { unsigned r; asm volatile("v_cvt_pk_bf16_f32 %0, %1, %2" : "=v"(r) : "v"(lo), "v"(hi)); return r; }
;     __device__ __forceinline__ void operator()(const f32x4 (&acc)[2][2][4][2], const Unit& u, int wr, int wc, int fr, int fq, int ui) const {
;     ...
;         const int row0 = u.pm * BM + wr * 64 + fr, col0 = u.pn * BM + wc * 32 + 8 * fq, lane = fq * 16 + fr;
; #pragma unroll
;         for (int ai = 0; ai < 2; ++ai)
; #pragma unroll
;             for (int m = 0; m < 4; ++m) { const int row = row0 + ai * HALF + m * 16; bf16_t* rowb = XB + (size_t)row * ldc + col0; float ss = 0.f;
; #pragma unroll
;                 for (int bj = 0; bj < 2; ++bj) { const f32x4 x0 = acc[ai][bj][m][0], x1 = acc[ai][bj][m][1];
;                     ss += ((x0[0] * x0[0] + x0[1] * x0[1]) + (x0[2] * x0[2] + x0[3] * x0[3])) + ((x1[0] * x1[0] + x1[1] * x1[1]) + (x1[2] * x1[2] + x1[3] * x1[3]));
;                     u32x4 w; w.x = cvt_pk_bf16(x0[0], x0[1]); w.y = cvt_pk_bf16(x0[2], x0[3]); w.z = cvt_pk_bf16(x1[0], x1[1]); w.w = cvt_pk_bf16(x1[2], x1[3]); store16_wt(rowb + bj * HALF, w); }
;                 ss += lane_get(ss, lane ^ 16); ss += lane_get(ss, lane ^ 32);
;                 if (fq == 0) __hip_atomic_store((unsigned*)stats + (size_t)row * 16 + u.pn * 4 + wc, __float_as_uint(ss), __ATOMIC_RELAXED, __HIP_MEMORY_SCOPE_AGENT); }
.LBB0_310:
	s_or_b64 exec, exec, s[34:35]
	v_add_u32_e32 v48, 0x90, v146
	s_waitcnt lgkmcnt(0)
	v_ashrrev_i32_e32 v49, 31, v48
	v_mul_f32_e32 v52, v25, v25
	v_lshlrev_b64 v[50:51], 11, v[48:49]
	v_fmac_f32_e32 v52, v24, v24
	v_mul_f32_e32 v53, v27, v27
	v_cvt_pk_bf16_f32 v24, v24, v25
	v_cvt_pk_bf16_f32 v25, v26, v27
	v_lshl_add_u64 v[50:51], v[144:145], 0, v[50:51]
	v_fmac_f32_e32 v53, v26, v26
	v_cvt_pk_bf16_f32 v26, v32, v33
	v_cvt_pk_bf16_f32 v27, v34, v35
	v_add_f32_e32 v52, v52, v53
	global_store_dwordx4 v[50:51], v[24:27], off sc1
	s_nop 1
	v_mul_f32_e32 v24, v29, v29
	v_mul_f32_e32 v25, v31, v31
	v_fmac_f32_e32 v24, v28, v28
	v_fmac_f32_e32 v25, v30, v30
	v_mul_f32_e32 v53, v33, v33
	v_mul_f32_e32 v54, v35, v35
	v_add_f32_e32 v24, v24, v25
	v_mul_f32_e32 v25, v37, v37
	v_mul_f32_e32 v26, v39, v39
	v_fmac_f32_e32 v53, v32, v32
	v_fmac_f32_e32 v54, v34, v34
	v_fmac_f32_e32 v25, v36, v36
	v_fmac_f32_e32 v26, v38, v38
	v_add_f32_e32 v53, v53, v54
	v_add_f32_e32 v25, v25, v26
	v_add_f32_e32 v52, v52, v53
	v_add_f32_e32 v24, v24, v25
	v_add_f32_e32 v24, v52, v24
	v_mov_b32_e32 v25, v24
	s_nop 1
	v_permlane16_swap_b32_e32 v25, v24
	v_cvt_pk_bf16_f32 v26, v28, v29
	v_cvt_pk_bf16_f32 v27, v30, v31
	v_cvt_pk_bf16_f32 v28, v36, v37
	v_cvt_pk_bf16_f32 v29, v38, v39
	s_waitcnt lgkmcnt(0)
	v_add_f32_e32 v24, v24, v25
	v_mov_b32_e32 v25, v24
	s_nop 1
	v_permlane32_swap_b32_e32 v25, v24
	v_lshl_add_u64 v[30:31], v[50:51], 0, s[26:27]
	global_store_dwordx4 v[30:31], v[26:29], off sc1
	s_nop 1
	s_and_saveexec_b64 s[34:35], s[2:3]
	s_cbranch_execz .LBB0_312
	v_lshlrev_b64 v[26:27], 6, v[48:49]
	v_lshl_add_u64 v[26:27], s[30:31], 0, v[26:27]
	s_waitcnt lgkmcnt(0)
	v_add_f32_e32 v24, v24, v25
	global_store_dword v[26:27], v24, off sc1
.LBB0_312:
	s_or_b64 exec, exec, s[34:35]
	v_add_u32_e32 v24, 0xa0, v146
	s_waitcnt lgkmcnt(0)
	v_ashrrev_i32_e32 v25, 31, v24
	v_mul_f32_e32 v28, v1, v1
	v_lshlrev_b64 v[26:27], 11, v[24:25]
	v_fmac_f32_e32 v28, v0, v0
	v_mul_f32_e32 v29, v3, v3
	v_cvt_pk_bf16_f32 v0, v0, v1
	v_cvt_pk_bf16_f32 v1, v2, v3
	v_lshl_add_u64 v[26:27], v[144:145], 0, v[26:27]
	v_fmac_f32_e32 v29, v2, v2
	v_cvt_pk_bf16_f32 v2, v4, v5
	v_cvt_pk_bf16_f32 v3, v6, v7
	v_add_f32_e32 v28, v28, v29
	global_store_dwordx4 v[26:27], v[0:3], off sc1
	s_nop 1
	v_mul_f32_e32 v0, v41, v41
	v_mul_f32_e32 v1, v43, v43
	v_fmac_f32_e32 v0, v40, v40
	v_fmac_f32_e32 v1, v42, v42
	v_mul_f32_e32 v29, v5, v5
	v_mul_f32_e32 v30, v7, v7
	v_add_f32_e32 v0, v0, v1
	v_mul_f32_e32 v1, v45, v45
	v_mul_f32_e32 v2, v47, v47
	v_fmac_f32_e32 v29, v4, v4
	v_fmac_f32_e32 v30, v6, v6
	v_fmac_f32_e32 v1, v44, v44
	v_fmac_f32_e32 v2, v46, v46
	v_add_f32_e32 v29, v29, v30
	v_add_f32_e32 v1, v1, v2
	v_add_f32_e32 v28, v28, v29
	v_add_f32_e32 v0, v0, v1
	v_add_f32_e32 v0, v28, v0
	v_mov_b32_e32 v1, v0
	s_nop 1
	v_permlane16_swap_b32_e32 v1, v0
	v_cvt_pk_bf16_f32 v2, v40, v41
	v_cvt_pk_bf16_f32 v3, v42, v43
	v_cvt_pk_bf16_f32 v4, v44, v45
	v_cvt_pk_bf16_f32 v5, v46, v47
	s_waitcnt lgkmcnt(0)
	v_add_f32_e32 v0, v0, v1
	v_mov_b32_e32 v1, v0
	s_nop 1
	v_permlane32_swap_b32_e32 v1, v0
	v_lshl_add_u64 v[6:7], v[26:27], 0, s[26:27]
	global_store_dwordx4 v[6:7], v[2:5], off sc1
	s_nop 1
	s_and_saveexec_b64 s[34:35], s[2:3]
	s_cbranch_execz .LBB0_314
	v_lshlrev_b64 v[2:3], 6, v[24:25]
	v_lshl_add_u64 v[2:3], s[30:31], 0, v[2:3]
	s_waitcnt lgkmcnt(0)
	v_add_f32_e32 v0, v0, v1
	global_store_dword v[2:3], v0, off sc1
.LBB0_314:
	s_or_b64 exec, exec, s[34:35]
	v_add_u32_e32 v0, 0xb0, v146
	s_waitcnt lgkmcnt(0)
	v_ashrrev_i32_e32 v1, 31, v0
	v_lshlrev_b64 v[2:3], 11, v[0:1]
	v_lshl_add_u64 v[24:25], v[144:145], 0, v[2:3]
	v_mul_f32_e32 v2, v9, v9
	v_mul_f32_e32 v3, v11, v11
	v_fmac_f32_e32 v2, v8, v8
	v_fmac_f32_e32 v3, v10, v10
	v_add_f32_e32 v2, v2, v3
	v_mul_f32_e32 v3, v17, v17
	v_mul_f32_e32 v4, v19, v19
	v_fmac_f32_e32 v3, v16, v16
	v_fmac_f32_e32 v4, v18, v18
	v_add_f32_e32 v3, v3, v4
	v_add_f32_e32 v6, v2, v3
	v_cvt_pk_bf16_f32 v2, v8, v9
	v_cvt_pk_bf16_f32 v3, v10, v11
	v_cvt_pk_bf16_f32 v4, v16, v17
	v_cvt_pk_bf16_f32 v5, v18, v19
	v_lshl_add_u64 v[8:9], v[24:25], 0, s[26:27]
	global_store_dwordx4 v[24:25], v[2:5], off sc1
	s_nop 1
	v_mul_f32_e32 v2, v13, v13
	v_mul_f32_e32 v3, v15, v15
	v_fmac_f32_e32 v2, v12, v12
	v_fmac_f32_e32 v3, v14, v14
	v_add_f32_e32 v2, v2, v3
	v_mul_f32_e32 v3, v21, v21
	v_mul_f32_e32 v4, v23, v23
	v_fmac_f32_e32 v3, v20, v20
	v_fmac_f32_e32 v4, v22, v22
	v_add_f32_e32 v3, v3, v4
	v_add_f32_e32 v2, v2, v3
	v_add_f32_e32 v2, v6, v2
	v_mov_b32_e32 v3, v2
	s_nop 1
	v_permlane16_swap_b32_e32 v3, v2
	v_cvt_pk_bf16_f32 v4, v12, v13
	v_cvt_pk_bf16_f32 v5, v14, v15
	v_cvt_pk_bf16_f32 v6, v20, v21
	v_cvt_pk_bf16_f32 v7, v22, v23
	s_waitcnt lgkmcnt(0)
	v_add_f32_e32 v2, v2, v3
	v_mov_b32_e32 v3, v2
	s_nop 1
	v_permlane32_swap_b32_e32 v3, v2
	global_store_dwordx4 v[8:9], v[4:7], off sc1
	s_nop 1
	s_and_saveexec_b64 s[34:35], s[2:3]
	s_cbranch_execz .LBB0_316
	v_lshlrev_b64 v[0:1], 6, v[0:1]
	v_lshl_add_u64 v[0:1], s[30:31], 0, v[0:1]
	s_waitcnt lgkmcnt(0)
	v_add_f32_e32 v2, v2, v3
	global_store_dword v[0:1], v2, off sc1

; __device__ __forceinline__ void store16_wt(void* p, wt_u32x4 v) { asm volatile("global_store_dwordx4 %0, %1, off sc1\n\ts_nop 1" :: "v"(p), "v"(v) : "memory"); }
; __device__ __forceinline__ float lane_get(float v, int src_lane) { return __builtin_bit_cast(float, __builtin_amdgcn_ds_bpermute(src_lane << 2, __builtin_bit_cast(int, v))); }
; __device__ __forceinline__ unsigned cvt_pk_bf16(float lo, float hi) { unsigned r; asm volatile("v_cvt_pk_bf16_f32 %0, %1, %2" : "=v"(r) : "v"(lo), "v"(hi)); return r; }
;     __device__ __forceinline__ void operator()(const f32x4 (&acc)[2][2][4][2], const Unit& u, int wr, int wc, int fr, int fq, int ui) const {
;     ...
;         const int row0 = u.pm * BM + wr * 64 + fr, col0 = u.pn * BM + wc * 32 + 8 * fq, lane = fq * 16 + fr;
; #pragma unroll
;         for (int ai = 0; ai < 2; ++ai)
; #pragma unroll
;             for (int m = 0; m < 4; ++m) { const int row = row0 + ai * HALF + m * 16; bf16_t* rowb = XB + (size_t)row * ldc + col0; float ss = 0.f;
; #pragma unroll
;                 for (int bj = 0; bj < 2; ++bj) { const f32x4 x0 = acc[ai][bj][m][0], x1 = acc[ai][bj][m][1];
;                     ss += ((x0[0] * x0[0] + x0[1] * x0[1]) + (x0[2] * x0[2] + x0[3] * x0[3])) + ((x1[0] * x1[0] + x1[1] * x1[1]) + (x1[2] * x1[2] + x1[3] * x1[3]));
;                     u32x4 w; w.x = cvt_pk_bf16(x0[0], x0[1]); w.y = cvt_pk_bf16(x0[2], x0[3]); w.z = cvt_pk_bf16(x1[0], x1[1]); w.w = cvt_pk_bf16(x1[2], x1[3]); store16_wt(rowb + bj * HALF, w); }
;                 ss += lane_get(ss, lane ^ 16); ss += lane_get(ss, lane ^ 32);
;                 if (fq == 0) __hip_atomic_store((unsigned*)stats + (size_t)row * 16 + u.pn * 4 + wc, __float_as_uint(ss), __ATOMIC_RELAXED, __HIP_MEMORY_SCOPE_AGENT); }
.LBB0_675:
	v_lshl_add_u32 v146, s72, 8, v148
	v_lshl_or_b32 v144, s36, 8, v152
	v_ashrrev_i32_e32 v145, 31, v144
	v_ashrrev_i32_e32 v147, 31, v146
	v_mul_f32_e32 v156, v113, v113
	v_lshl_add_u64 v[144:145], v[144:145], 1, s[10:11]
	v_lshlrev_b64 v[154:155], 11, v[146:147]
	v_fmac_f32_e32 v156, v112, v112
	v_mul_f32_e32 v157, v115, v115
	v_cvt_pk_bf16_f32 v112, v112, v113
	v_cvt_pk_bf16_f32 v113, v114, v115
	v_lshl_add_u64 v[154:155], v[144:145], 0, v[154:155]
	v_fmac_f32_e32 v157, v114, v114
	v_cvt_pk_bf16_f32 v114, v120, v121
	v_cvt_pk_bf16_f32 v115, v122, v123
	v_add_f32_e32 v156, v156, v157
	global_store_dwordx4 v[154:155], v[112:115], off sc1
	s_nop 1
	v_mul_f32_e32 v112, v117, v117
	v_mul_f32_e32 v113, v119, v119
	v_fmac_f32_e32 v112, v116, v116
	v_fmac_f32_e32 v113, v118, v118
	v_mul_f32_e32 v157, v121, v121
	v_mul_f32_e32 v158, v123, v123
	v_add_f32_e32 v112, v112, v113
	v_mul_f32_e32 v113, v125, v125
	v_mul_f32_e32 v114, v127, v127
	v_fmac_f32_e32 v157, v120, v120
	v_fmac_f32_e32 v158, v122, v122
	v_fmac_f32_e32 v113, v124, v124
	v_fmac_f32_e32 v114, v126, v126
	v_add_f32_e32 v157, v157, v158
	v_add_f32_e32 v113, v113, v114
	v_add_f32_e32 v156, v156, v157
	v_add_f32_e32 v112, v112, v113
	v_add_f32_e32 v112, v156, v112
	v_mov_b32_e32 v113, v112
	s_nop 1
	v_permlane16_swap_b32_e32 v113, v112
	s_lshl_b32 s6, s36, 2
	s_ashr_i32 s7, s6, 31
	s_lshl_b64 s[6:7], s[6:7], 2
	v_cvt_pk_bf16_f32 v114, v116, v117
	s_waitcnt lgkmcnt(0)
	v_add_f32_e32 v112, v112, v113
	v_mov_b32_e32 v113, v112
	s_nop 1
	v_permlane32_swap_b32_e32 v113, v112
	v_cvt_pk_bf16_f32 v115, v118, v119
	v_cvt_pk_bf16_f32 v116, v124, v125
	v_cvt_pk_bf16_f32 v117, v126, v127
	v_lshl_add_u64 v[118:119], v[154:155], 0, s[26:27]
	global_store_dwordx4 v[118:119], v[114:117], off sc1
	s_nop 1
	s_add_u32 s6, s66, s6
	s_addc_u32 s7, s67, s7
	s_and_saveexec_b64 s[36:37], s[2:3]
	s_cbranch_execz .LBB0_677
	v_lshlrev_b64 v[114:115], 6, v[146:147]
	v_lshl_add_u64 v[114:115], s[6:7], 0, v[114:115]
	s_waitcnt lgkmcnt(0)
	v_add_f32_e32 v112, v112, v113
	global_store_dword v[114:115], v112, off sc1
.LBB0_677:
	s_or_b64 exec, exec, s[36:37]
	v_or_b32_e32 v112, 16, v146
	s_waitcnt lgkmcnt(0)
	v_ashrrev_i32_e32 v113, 31, v112
	v_mul_f32_e32 v116, v97, v97
	v_lshlrev_b64 v[114:115], 11, v[112:113]
	v_fmac_f32_e32 v116, v96, v96
	v_mul_f32_e32 v117, v99, v99
	v_cvt_pk_bf16_f32 v96, v96, v97
	v_cvt_pk_bf16_f32 v97, v98, v99
	v_lshl_add_u64 v[114:115], v[144:145], 0, v[114:115]
	v_fmac_f32_e32 v117, v98, v98
	v_cvt_pk_bf16_f32 v98, v104, v105
	v_cvt_pk_bf16_f32 v99, v106, v107
	v_add_f32_e32 v116, v116, v117
	global_store_dwordx4 v[114:115], v[96:99], off sc1
	s_nop 1
	v_mul_f32_e32 v96, v101, v101
	v_mul_f32_e32 v97, v103, v103
	v_fmac_f32_e32 v96, v100, v100
	v_fmac_f32_e32 v97, v102, v102
	v_mul_f32_e32 v117, v105, v105
	v_mul_f32_e32 v118, v107, v107
	v_add_f32_e32 v96, v96, v97
	v_mul_f32_e32 v97, v109, v109
	v_mul_f32_e32 v98, v111, v111
	v_fmac_f32_e32 v117, v104, v104
	v_fmac_f32_e32 v118, v106, v106
	v_fmac_f32_e32 v97, v108, v108
	v_fmac_f32_e32 v98, v110, v110
	v_add_f32_e32 v117, v117, v118
	v_add_f32_e32 v97, v97, v98
	v_add_f32_e32 v116, v116, v117
	v_add_f32_e32 v96, v96, v97
	v_add_f32_e32 v96, v116, v96
	v_mov_b32_e32 v97, v96
	s_nop 1
	v_permlane16_swap_b32_e32 v97, v96
	v_cvt_pk_bf16_f32 v98, v100, v101
	v_cvt_pk_bf16_f32 v99, v102, v103
	v_cvt_pk_bf16_f32 v100, v108, v109
	v_cvt_pk_bf16_f32 v101, v110, v111
	s_waitcnt lgkmcnt(0)
	v_add_f32_e32 v96, v96, v97
	v_mov_b32_e32 v97, v96
	s_nop 1
	v_permlane32_swap_b32_e32 v97, v96
	v_lshl_add_u64 v[102:103], v[114:115], 0, s[26:27]
	global_store_dwordx4 v[102:103], v[98:101], off sc1
	s_nop 1
	s_and_saveexec_b64 s[36:37], s[2:3]
	s_cbranch_execz .LBB0_679
	v_lshlrev_b64 v[98:99], 6, v[112:113]
	v_lshl_add_u64 v[98:99], s[6:7], 0, v[98:99]
	s_waitcnt lgkmcnt(0)
	v_add_f32_e32 v96, v96, v97
	global_store_dword v[98:99], v96, off sc1
.LBB0_679:
	s_or_b64 exec, exec, s[36:37]
	v_or_b32_e32 v96, 32, v146
	s_waitcnt lgkmcnt(0)
	v_ashrrev_i32_e32 v97, 31, v96
	v_mul_f32_e32 v100, v81, v81
	v_lshlrev_b64 v[98:99], 11, v[96:97]
	v_fmac_f32_e32 v100, v80, v80
	v_mul_f32_e32 v101, v83, v83
	v_cvt_pk_bf16_f32 v80, v80, v81
	v_cvt_pk_bf16_f32 v81, v82, v83
	v_lshl_add_u64 v[98:99], v[144:145], 0, v[98:99]
	v_fmac_f32_e32 v101, v82, v82
	v_cvt_pk_bf16_f32 v82, v88, v89
	v_cvt_pk_bf16_f32 v83, v90, v91
	v_add_f32_e32 v100, v100, v101
	global_store_dwordx4 v[98:99], v[80:83], off sc1
	s_nop 1
	v_mul_f32_e32 v80, v85, v85
	v_mul_f32_e32 v81, v87, v87
	v_fmac_f32_e32 v80, v84, v84
	v_fmac_f32_e32 v81, v86, v86
	v_mul_f32_e32 v101, v89, v89
	v_mul_f32_e32 v102, v91, v91
	v_add_f32_e32 v80, v80, v81
	v_mul_f32_e32 v81, v93, v93
	v_mul_f32_e32 v82, v95, v95
	v_fmac_f32_e32 v101, v88, v88
	v_fmac_f32_e32 v102, v90, v90
	v_fmac_f32_e32 v81, v92, v92
	v_fmac_f32_e32 v82, v94, v94
	v_add_f32_e32 v101, v101, v102
	v_add_f32_e32 v81, v81, v82
	v_add_f32_e32 v100, v100, v101
	v_add_f32_e32 v80, v80, v81
	v_add_f32_e32 v80, v100, v80
	v_mov_b32_e32 v81, v80
	s_nop 1
	v_permlane16_swap_b32_e32 v81, v80
	v_cvt_pk_bf16_f32 v82, v84, v85
	v_cvt_pk_bf16_f32 v83, v86, v87
	v_cvt_pk_bf16_f32 v84, v92, v93
	v_cvt_pk_bf16_f32 v85, v94, v95
	s_waitcnt lgkmcnt(0)
	v_add_f32_e32 v80, v80, v81
	v_mov_b32_e32 v81, v80
	s_nop 1
	v_permlane32_swap_b32_e32 v81, v80
	v_lshl_add_u64 v[86:87], v[98:99], 0, s[26:27]
	global_store_dwordx4 v[86:87], v[82:85], off sc1
	s_nop 1
	s_and_saveexec_b64 s[36:37], s[2:3]
	s_cbranch_execz .LBB0_681
	v_lshlrev_b64 v[82:83], 6, v[96:97]
	v_lshl_add_u64 v[82:83], s[6:7], 0, v[82:83]
	s_waitcnt lgkmcnt(0)
	v_add_f32_e32 v80, v80, v81
	global_store_dword v[82:83], v80, off sc1
; __device__ __forceinline__ void store16_wt(void* p, wt_u32x4 v) { asm volatile("global_store_dwordx4 %0, %1, off sc1\n\ts_nop 1" :: "v"(p), "v"(v) : "memory"); }
; __device__ __forceinline__ float lane_get(float v, int src_lane) { return __builtin_bit_cast(float, __builtin_amdgcn_ds_bpermute(src_lane << 2, __builtin_bit_cast(int, v))); }
; __device__ __forceinline__ unsigned cvt_pk_bf16(float lo, float hi) { unsigned r; asm volatile("v_cvt_pk_bf16_f32 %0, %1, %2" : "=v"(r) : "v"(lo), "v"(hi)); return r; }
;     __device__ __forceinline__ void operator()(const f32x4 (&acc)[2][2][4][2], const Unit& u, int wr, int wc, int fr, int fq, int ui) const {
;     ...
;         const int row0 = u.pm * BM + wr * 64 + fr, col0 = u.pn * BM + wc * 32 + 8 * fq, lane = fq * 16 + fr;
; #pragma unroll
;         for (int ai = 0; ai < 2; ++ai)
; #pragma unroll
;             for (int m = 0; m < 4; ++m) { const int row = row0 + ai * HALF + m * 16; bf16_t* rowb = XB + (size_t)row * ldc + col0; float ss = 0.f;
; #pragma unroll
;                 for (int bj = 0; bj < 2; ++bj) { const f32x4 x0 = acc[ai][bj][m][0], x1 = acc[ai][bj][m][1];
;                     ss += ((x0[0] * x0[0] + x0[1] * x0[1]) + (x0[2] * x0[2] + x0[3] * x0[3])) + ((x1[0] * x1[0] + x1[1] * x1[1]) + (x1[2] * x1[2] + x1[3] * x1[3]));
;                     u32x4 w; w.x = cvt_pk_bf16(x0[0], x0[1]); w.y = cvt_pk_bf16(x0[2], x0[3]); w.z = cvt_pk_bf16(x1[0], x1[1]); w.w = cvt_pk_bf16(x1[2], x1[3]); store16_wt(rowb + bj * HALF, w); }
;                 ss += lane_get(ss, lane ^ 16); ss += lane_get(ss, lane ^ 32);
;                 if (fq == 0) __hip_atomic_store((unsigned*)stats + (size_t)row * 16 + u.pn * 4 + wc, __float_as_uint(ss), __ATOMIC_RELAXED, __HIP_MEMORY_SCOPE_AGENT); }
.LBB0_681:
	s_or_b64 exec, exec, s[36:37]
	v_or_b32_e32 v80, 48, v146
	s_waitcnt lgkmcnt(0)
	v_ashrrev_i32_e32 v81, 31, v80
	v_mul_f32_e32 v84, v65, v65
	v_lshlrev_b64 v[82:83], 11, v[80:81]
	v_fmac_f32_e32 v84, v64, v64
	v_mul_f32_e32 v85, v67, v67
	v_cvt_pk_bf16_f32 v64, v64, v65
	v_cvt_pk_bf16_f32 v65, v66, v67
	v_lshl_add_u64 v[82:83], v[144:145], 0, v[82:83]
	v_fmac_f32_e32 v85, v66, v66
	v_cvt_pk_bf16_f32 v66, v72, v73
	v_cvt_pk_bf16_f32 v67, v74, v75
	v_add_f32_e32 v84, v84, v85
	global_store_dwordx4 v[82:83], v[64:67], off sc1
	s_nop 1
	v_mul_f32_e32 v64, v69, v69
	v_mul_f32_e32 v65, v71, v71
	v_fmac_f32_e32 v64, v68, v68
	v_fmac_f32_e32 v65, v70, v70
	v_mul_f32_e32 v85, v73, v73
	v_mul_f32_e32 v86, v75, v75
	v_add_f32_e32 v64, v64, v65
	v_mul_f32_e32 v65, v77, v77
	v_mul_f32_e32 v66, v79, v79
	v_fmac_f32_e32 v85, v72, v72
	v_fmac_f32_e32 v86, v74, v74
	v_fmac_f32_e32 v65, v76, v76
	v_fmac_f32_e32 v66, v78, v78
	v_add_f32_e32 v85, v85, v86
	v_add_f32_e32 v65, v65, v66
	v_add_f32_e32 v84, v84, v85
	v_add_f32_e32 v64, v64, v65
	v_add_f32_e32 v64, v84, v64
	v_mov_b32_e32 v65, v64
	s_nop 1
	v_permlane16_swap_b32_e32 v65, v64
	v_cvt_pk_bf16_f32 v66, v68, v69
	v_cvt_pk_bf16_f32 v67, v70, v71
	v_cvt_pk_bf16_f32 v68, v76, v77
	v_cvt_pk_bf16_f32 v69, v78, v79
	s_waitcnt lgkmcnt(0)
	v_add_f32_e32 v64, v64, v65
	v_mov_b32_e32 v65, v64
	s_nop 1
	v_permlane32_swap_b32_e32 v65, v64
	v_lshl_add_u64 v[70:71], v[82:83], 0, s[26:27]
	global_store_dwordx4 v[70:71], v[66:69], off sc1
	s_nop 1
	s_and_saveexec_b64 s[36:37], s[2:3]
	s_cbranch_execz .LBB0_683
	v_lshlrev_b64 v[66:67], 6, v[80:81]
	v_lshl_add_u64 v[66:67], s[6:7], 0, v[66:67]
	s_waitcnt lgkmcnt(0)
	v_add_f32_e32 v64, v64, v65
	global_store_dword v[66:67], v64, off sc1
.LBB0_683:
	s_or_b64 exec, exec, s[36:37]
	v_add_u32_e32 v64, 0x80, v146
	s_waitcnt lgkmcnt(0)
	v_ashrrev_i32_e32 v65, 31, v64
	v_mul_f32_e32 v68, v49, v49
	v_lshlrev_b64 v[66:67], 11, v[64:65]
	v_fmac_f32_e32 v68, v48, v48
	v_mul_f32_e32 v69, v51, v51
	v_cvt_pk_bf16_f32 v48, v48, v49
	v_cvt_pk_bf16_f32 v49, v50, v51
	v_lshl_add_u64 v[66:67], v[144:145], 0, v[66:67]
	v_fmac_f32_e32 v69, v50, v50
	v_cvt_pk_bf16_f32 v50, v56, v57
	v_cvt_pk_bf16_f32 v51, v58, v59
	v_add_f32_e32 v68, v68, v69
	global_store_dwordx4 v[66:67], v[48:51], off sc1
	s_nop 1
	v_mul_f32_e32 v48, v53, v53
	v_mul_f32_e32 v49, v55, v55
	v_fmac_f32_e32 v48, v52, v52
	v_fmac_f32_e32 v49, v54, v54
	v_mul_f32_e32 v69, v57, v57
	v_mul_f32_e32 v70, v59, v59
	v_add_f32_e32 v48, v48, v49
	v_mul_f32_e32 v49, v61, v61
	v_mul_f32_e32 v50, v63, v63
	v_fmac_f32_e32 v69, v56, v56
	v_fmac_f32_e32 v70, v58, v58
	v_fmac_f32_e32 v49, v60, v60
	v_fmac_f32_e32 v50, v62, v62
	v_add_f32_e32 v69, v69, v70
	v_add_f32_e32 v49, v49, v50
	v_add_f32_e32 v68, v68, v69
	v_add_f32_e32 v48, v48, v49
	v_add_f32_e32 v48, v68, v48
	v_mov_b32_e32 v49, v48
	s_nop 1
	v_permlane16_swap_b32_e32 v49, v48
	v_cvt_pk_bf16_f32 v50, v52, v53
	v_cvt_pk_bf16_f32 v51, v54, v55
	v_cvt_pk_bf16_f32 v52, v60, v61
	v_cvt_pk_bf16_f32 v53, v62, v63
	s_waitcnt lgkmcnt(0)
	v_add_f32_e32 v48, v48, v49
	v_mov_b32_e32 v49, v48
	s_nop 1
	v_permlane32_swap_b32_e32 v49, v48
	v_lshl_add_u64 v[54:55], v[66:67], 0, s[26:27]
	global_store_dwordx4 v[54:55], v[50:53], off sc1
	s_nop 1
	s_and_saveexec_b64 s[36:37], s[2:3]
	s_cbranch_execz .LBB0_685
	v_lshlrev_b64 v[50:51], 6, v[64:65]
	v_lshl_add_u64 v[50:51], s[6:7], 0, v[50:51]
	s_waitcnt lgkmcnt(0)
	v_add_f32_e32 v48, v48, v49
	global_store_dword v[50:51], v48, off sc1
; __device__ __forceinline__ void store16_wt(void* p, wt_u32x4 v) { asm volatile("global_store_dwordx4 %0, %1, off sc1\n\ts_nop 1" :: "v"(p), "v"(v) : "memory"); }
; __device__ __forceinline__ float lane_get(float v, int src_lane) { return __builtin_bit_cast(float, __builtin_amdgcn_ds_bpermute(src_lane << 2, __builtin_bit_cast(int, v))); }
; __device__ __forceinline__ unsigned cvt_pk_bf16(float lo, float hi) { unsigned r; asm volatile("v_cvt_pk_bf16_f32 %0, %1, %2" : "=v"(r) : "v"(lo), "v"(hi)); return r; }
;     __device__ __forceinline__ void operator()(const f32x4 (&acc)[2][2][4][2], const Unit& u, int wr, int wc, int fr, int fq, int ui) const {
;     ...
;         const int row0 = u.pm * BM + wr * 64 + fr, col0 = u.pn * BM + wc * 32 + 8 * fq, lane = fq * 16 + fr;
; #pragma unroll
;         for (int ai = 0; ai < 2; ++ai)
; #pragma unroll
;             for (int m = 0; m < 4; ++m) { const int row = row0 + ai * HALF + m * 16; bf16_t* rowb = XB + (size_t)row * ldc + col0; float ss = 0.f;
; #pragma unroll
;                 for (int bj = 0; bj < 2; ++bj) { const f32x4 x0 = acc[ai][bj][m][0], x1 = acc[ai][bj][m][1];
;                     ss += ((x0[0] * x0[0] + x0[1] * x0[1]) + (x0[2] * x0[2] + x0[3] * x0[3])) + ((x1[0] * x1[0] + x1[1] * x1[1]) + (x1[2] * x1[2] + x1[3] * x1[3]));
;                     u32x4 w; w.x = cvt_pk_bf16(x0[0], x0[1]); w.y = cvt_pk_bf16(x0[2], x0[3]); w.z = cvt_pk_bf16(x1[0], x1[1]); w.w = cvt_pk_bf16(x1[2], x1[3]); store16_wt(rowb + bj * HALF, w); }
;                 ss += lane_get(ss, lane ^ 16); ss += lane_get(ss, lane ^ 32);
;                 if (fq == 0) __hip_atomic_store((unsigned*)stats + (size_t)row * 16 + u.pn * 4 + wc, __float_as_uint(ss), __ATOMIC_RELAXED, __HIP_MEMORY_SCOPE_AGENT); }
.LBB0_685:
	s_or_b64 exec, exec, s[36:37]
	v_add_u32_e32 v48, 0x90, v146
	s_waitcnt lgkmcnt(0)
	v_ashrrev_i32_e32 v49, 31, v48
	v_mul_f32_e32 v52, v25, v25
	v_lshlrev_b64 v[50:51], 11, v[48:49]
	v_fmac_f32_e32 v52, v24, v24
	v_mul_f32_e32 v53, v27, v27
	v_cvt_pk_bf16_f32 v24, v24, v25
	v_cvt_pk_bf16_f32 v25, v26, v27
	v_lshl_add_u64 v[50:51], v[144:145], 0, v[50:51]
	v_fmac_f32_e32 v53, v26, v26
	v_cvt_pk_bf16_f32 v26, v32, v33
	v_cvt_pk_bf16_f32 v27, v34, v35
	v_add_f32_e32 v52, v52, v53
	global_store_dwordx4 v[50:51], v[24:27], off sc1
	s_nop 1
	v_mul_f32_e32 v24, v29, v29
	v_mul_f32_e32 v25, v31, v31
	v_fmac_f32_e32 v24, v28, v28
	v_fmac_f32_e32 v25, v30, v30
	v_mul_f32_e32 v53, v33, v33
	v_mul_f32_e32 v54, v35, v35
	v_add_f32_e32 v24, v24, v25
	v_mul_f32_e32 v25, v37, v37
	v_mul_f32_e32 v26, v39, v39
	v_fmac_f32_e32 v53, v32, v32
	v_fmac_f32_e32 v54, v34, v34
	v_fmac_f32_e32 v25, v36, v36
	v_fmac_f32_e32 v26, v38, v38
	v_add_f32_e32 v53, v53, v54
	v_add_f32_e32 v25, v25, v26
	v_add_f32_e32 v52, v52, v53
	v_add_f32_e32 v24, v24, v25
	v_add_f32_e32 v24, v52, v24
	v_mov_b32_e32 v25, v24
	s_nop 1
	v_permlane16_swap_b32_e32 v25, v24
	v_cvt_pk_bf16_f32 v26, v28, v29
	v_cvt_pk_bf16_f32 v27, v30, v31
	v_cvt_pk_bf16_f32 v28, v36, v37
	v_cvt_pk_bf16_f32 v29, v38, v39
	s_waitcnt lgkmcnt(0)
	v_add_f32_e32 v24, v24, v25
	v_mov_b32_e32 v25, v24
	s_nop 1
	v_permlane32_swap_b32_e32 v25, v24
	v_lshl_add_u64 v[30:31], v[50:51], 0, s[26:27]
	global_store_dwordx4 v[30:31], v[26:29], off sc1
	s_nop 1
	s_and_saveexec_b64 s[36:37], s[2:3]
	s_cbranch_execz .LBB0_687
	v_lshlrev_b64 v[26:27], 6, v[48:49]
	v_lshl_add_u64 v[26:27], s[6:7], 0, v[26:27]
	s_waitcnt lgkmcnt(0)
	v_add_f32_e32 v24, v24, v25
	global_store_dword v[26:27], v24, off sc1
.LBB0_687:
	s_or_b64 exec, exec, s[36:37]
	v_add_u32_e32 v24, 0xa0, v146
	s_waitcnt lgkmcnt(0)
	v_ashrrev_i32_e32 v25, 31, v24
	v_mul_f32_e32 v28, v1, v1
	v_lshlrev_b64 v[26:27], 11, v[24:25]
	v_fmac_f32_e32 v28, v0, v0
	v_mul_f32_e32 v29, v3, v3
	v_cvt_pk_bf16_f32 v0, v0, v1
	v_cvt_pk_bf16_f32 v1, v2, v3
	v_lshl_add_u64 v[26:27], v[144:145], 0, v[26:27]
	v_fmac_f32_e32 v29, v2, v2
	v_cvt_pk_bf16_f32 v2, v4, v5
	v_cvt_pk_bf16_f32 v3, v6, v7
	v_add_f32_e32 v28, v28, v29
	global_store_dwordx4 v[26:27], v[0:3], off sc1
	s_nop 1
	v_mul_f32_e32 v0, v41, v41
	v_mul_f32_e32 v1, v43, v43
	v_fmac_f32_e32 v0, v40, v40
	v_fmac_f32_e32 v1, v42, v42
	v_mul_f32_e32 v29, v5, v5
	v_mul_f32_e32 v30, v7, v7
	v_add_f32_e32 v0, v0, v1
	v_mul_f32_e32 v1, v45, v45
	v_mul_f32_e32 v2, v47, v47
	v_fmac_f32_e32 v29, v4, v4
	v_fmac_f32_e32 v30, v6, v6
	v_fmac_f32_e32 v1, v44, v44
	v_fmac_f32_e32 v2, v46, v46
	v_add_f32_e32 v29, v29, v30
	v_add_f32_e32 v1, v1, v2
	v_add_f32_e32 v28, v28, v29
	v_add_f32_e32 v0, v0, v1
	v_add_f32_e32 v0, v28, v0
	v_mov_b32_e32 v1, v0
	s_nop 1
	v_permlane16_swap_b32_e32 v1, v0
	v_cvt_pk_bf16_f32 v2, v40, v41
	v_cvt_pk_bf16_f32 v3, v42, v43
	v_cvt_pk_bf16_f32 v4, v44, v45
	v_cvt_pk_bf16_f32 v5, v46, v47
	s_waitcnt lgkmcnt(0)
	v_add_f32_e32 v0, v0, v1
	v_mov_b32_e32 v1, v0
	s_nop 1
	v_permlane32_swap_b32_e32 v1, v0
	v_lshl_add_u64 v[6:7], v[26:27], 0, s[26:27]
	global_store_dwordx4 v[6:7], v[2:5], off sc1
	s_nop 1
	s_and_saveexec_b64 s[36:37], s[2:3]
	s_cbranch_execz .LBB0_689
	v_lshlrev_b64 v[2:3], 6, v[24:25]
	v_lshl_add_u64 v[2:3], s[6:7], 0, v[2:3]
	s_waitcnt lgkmcnt(0)
	v_add_f32_e32 v0, v0, v1
	global_store_dword v[2:3], v0, off sc1
.LBB0_689:
	s_or_b64 exec, exec, s[36:37]
	v_add_u32_e32 v0, 0xb0, v146
	s_waitcnt lgkmcnt(0)
	v_ashrrev_i32_e32 v1, 31, v0
	v_lshlrev_b64 v[2:3], 11, v[0:1]
	v_lshl_add_u64 v[24:25], v[144:145], 0, v[2:3]
	v_mul_f32_e32 v2, v9, v9
	v_mul_f32_e32 v3, v11, v11
	v_fmac_f32_e32 v2, v8, v8
	v_fmac_f32_e32 v3, v10, v10
	v_add_f32_e32 v2, v2, v3
	v_mul_f32_e32 v3, v17, v17
	v_mul_f32_e32 v4, v19, v19
	v_fmac_f32_e32 v3, v16, v16
	v_fmac_f32_e32 v4, v18, v18
	v_add_f32_e32 v3, v3, v4
	v_add_f32_e32 v6, v2, v3
	v_cvt_pk_bf16_f32 v2, v8, v9
	v_cvt_pk_bf16_f32 v3, v10, v11
	v_cvt_pk_bf16_f32 v4, v16, v17
	v_cvt_pk_bf16_f32 v5, v18, v19
	v_lshl_add_u64 v[8:9], v[24:25], 0, s[26:27]
	global_store_dwordx4 v[24:25], v[2:5], off sc1
	s_nop 1
	v_mul_f32_e32 v2, v13, v13
	v_mul_f32_e32 v3, v15, v15
	v_fmac_f32_e32 v2, v12, v12
	v_fmac_f32_e32 v3, v14, v14
	v_add_f32_e32 v2, v2, v3
	v_mul_f32_e32 v3, v21, v21
	v_mul_f32_e32 v4, v23, v23
	v_fmac_f32_e32 v3, v20, v20
	v_fmac_f32_e32 v4, v22, v22
	v_add_f32_e32 v3, v3, v4
	v_add_f32_e32 v2, v2, v3
	v_add_f32_e32 v2, v6, v2
	v_mov_b32_e32 v3, v2
	s_nop 1
	v_permlane16_swap_b32_e32 v3, v2
	v_cvt_pk_bf16_f32 v4, v12, v13
	v_cvt_pk_bf16_f32 v5, v14, v15
	v_cvt_pk_bf16_f32 v6, v20, v21
	v_cvt_pk_bf16_f32 v7, v22, v23
	s_waitcnt lgkmcnt(0)
	v_add_f32_e32 v2, v2, v3
	v_mov_b32_e32 v3, v2
	s_nop 1
	v_permlane32_swap_b32_e32 v3, v2
	global_store_dwordx4 v[8:9], v[4:7], off sc1
	s_nop 1
	s_and_saveexec_b64 s[36:37], s[2:3]
	s_cbranch_execz .LBB0_691
	v_lshlrev_b64 v[0:1], 6, v[0:1]
	v_lshl_add_u64 v[0:1], s[6:7], 0, v[0:1]
	s_waitcnt lgkmcnt(0)
	v_add_f32_e32 v2, v2, v3
	global_store_dword v[0:1], v2, off sc1

; __device__ __forceinline__ void store16_wt(void* p, wt_u32x4 v) { asm volatile("global_store_dwordx4 %0, %1, off sc1\n\ts_nop 1" :: "v"(p), "v"(v) : "memory"); }
; __device__ __forceinline__ float lane_get(float v, int src_lane) { return __builtin_bit_cast(float, __builtin_amdgcn_ds_bpermute(src_lane << 2, __builtin_bit_cast(int, v))); }
; __device__ __forceinline__ unsigned cvt_pk_bf16(float lo, float hi) { unsigned r; asm volatile("v_cvt_pk_bf16_f32 %0, %1, %2" : "=v"(r) : "v"(lo), "v"(hi)); return r; }
;     __device__ __forceinline__ void operator()(const f32x4 (&acc)[2][2][4][2], const Unit& u, int wr, int wc, int fr, int fq, int ui) const {
;     ...
;         const int row0 = u.pm * BM + wr * 64 + fr, col0 = u.pn * BM + wc * 32 + 8 * fq, lane = fq * 16 + fr;
; #pragma unroll
;         for (int ai = 0; ai < 2; ++ai)
; #pragma unroll
;             for (int m = 0; m < 4; ++m) { const int row = row0 + ai * HALF + m * 16; bf16_t* rowb = XB + (size_t)row * ldc + col0; float ss = 0.f;
; #pragma unroll
;                 for (int bj = 0; bj < 2; ++bj) { const f32x4 x0 = acc[ai][bj][m][0], x1 = acc[ai][bj][m][1];
;                     ss += ((x0[0] * x0[0] + x0[1] * x0[1]) + (x0[2] * x0[2] + x0[3] * x0[3])) + ((x1[0] * x1[0] + x1[1] * x1[1]) + (x1[2] * x1[2] + x1[3] * x1[3]));
;                     u32x4 w; w.x = cvt_pk_bf16(x0[0], x0[1]); w.y = cvt_pk_bf16(x0[2], x0[3]); w.z = cvt_pk_bf16(x1[0], x1[1]); w.w = cvt_pk_bf16(x1[2], x1[3]); store16_wt(rowb + bj * HALF, w); }
;                 ss += lane_get(ss, lane ^ 16); ss += lane_get(ss, lane ^ 32);
;                 if (fq == 0) __hip_atomic_store((unsigned*)stats + (size_t)row * 16 + u.pn * 4 + wc, __float_as_uint(ss), __ATOMIC_RELAXED, __HIP_MEMORY_SCOPE_AGENT); }
.LBB0_889:
	v_lshl_add_u32 v138, s40, 8, v148
	v_lshl_or_b32 v136, s38, 8, v152
	v_ashrrev_i32_e32 v137, 31, v136
	v_ashrrev_i32_e32 v139, 31, v138
	v_mul_f32_e32 v156, v113, v113
	v_lshl_add_u64 v[136:137], v[136:137], 1, s[12:13]
	v_lshlrev_b64 v[154:155], 11, v[138:139]
	v_fmac_f32_e32 v156, v112, v112
	v_mul_f32_e32 v157, v115, v115
	v_cvt_pk_bf16_f32 v112, v112, v113
	v_cvt_pk_bf16_f32 v113, v114, v115
	v_lshl_add_u64 v[154:155], v[136:137], 0, v[154:155]
	v_fmac_f32_e32 v157, v114, v114
	v_cvt_pk_bf16_f32 v114, v120, v121
	v_cvt_pk_bf16_f32 v115, v122, v123
	v_add_f32_e32 v156, v156, v157
	global_store_dwordx4 v[154:155], v[112:115], off sc1
	s_nop 1
	v_mul_f32_e32 v112, v117, v117
	v_mul_f32_e32 v113, v119, v119
	v_fmac_f32_e32 v112, v116, v116
	v_fmac_f32_e32 v113, v118, v118
	v_mul_f32_e32 v157, v121, v121
	v_mul_f32_e32 v158, v123, v123
	v_add_f32_e32 v112, v112, v113
	v_mul_f32_e32 v113, v125, v125
	v_mul_f32_e32 v114, v127, v127
	v_fmac_f32_e32 v157, v120, v120
	v_fmac_f32_e32 v158, v122, v122
	v_fmac_f32_e32 v113, v124, v124
	v_fmac_f32_e32 v114, v126, v126
	v_add_f32_e32 v157, v157, v158
	v_add_f32_e32 v113, v113, v114
	v_add_f32_e32 v156, v156, v157
	v_add_f32_e32 v112, v112, v113
	v_add_f32_e32 v112, v156, v112
	v_mov_b32_e32 v113, v112
	s_nop 1
	v_permlane16_swap_b32_e32 v113, v112
	s_lshl_b32 s38, s38, 2
	s_ashr_i32 s39, s38, 31
	s_lshl_b64 s[38:39], s[38:39], 2
	v_cvt_pk_bf16_f32 v114, v116, v117
	s_waitcnt lgkmcnt(0)
	v_add_f32_e32 v112, v112, v113
	v_mov_b32_e32 v113, v112
	s_nop 1
	v_permlane32_swap_b32_e32 v113, v112
	v_cvt_pk_bf16_f32 v115, v118, v119
	v_cvt_pk_bf16_f32 v116, v124, v125
	v_cvt_pk_bf16_f32 v117, v126, v127
	v_lshl_add_u64 v[118:119], v[154:155], 0, s[14:15]
	global_store_dwordx4 v[118:119], v[114:117], off sc1
	s_nop 1
	s_add_u32 s38, s64, s38
	s_addc_u32 s39, s65, s39
	s_and_saveexec_b64 s[40:41], s[2:3]
	s_cbranch_execz .LBB0_891
	v_lshlrev_b64 v[114:115], 6, v[138:139]
	v_lshl_add_u64 v[114:115], s[38:39], 0, v[114:115]
	s_waitcnt lgkmcnt(0)
	v_add_f32_e32 v112, v112, v113
	global_store_dword v[114:115], v112, off sc1
.LBB0_891:
	s_or_b64 exec, exec, s[40:41]
	v_or_b32_e32 v112, 16, v138
	s_waitcnt lgkmcnt(0)
	v_ashrrev_i32_e32 v113, 31, v112
	v_mul_f32_e32 v116, v97, v97
	v_lshlrev_b64 v[114:115], 11, v[112:113]
	v_fmac_f32_e32 v116, v96, v96
	v_mul_f32_e32 v117, v99, v99
	v_cvt_pk_bf16_f32 v96, v96, v97
	v_cvt_pk_bf16_f32 v97, v98, v99
	v_lshl_add_u64 v[114:115], v[136:137], 0, v[114:115]
	v_fmac_f32_e32 v117, v98, v98
	v_cvt_pk_bf16_f32 v98, v104, v105
	v_cvt_pk_bf16_f32 v99, v106, v107
	v_add_f32_e32 v116, v116, v117
	global_store_dwordx4 v[114:115], v[96:99], off sc1
	s_nop 1
	v_mul_f32_e32 v96, v101, v101
	v_mul_f32_e32 v97, v103, v103
	v_fmac_f32_e32 v96, v100, v100
	v_fmac_f32_e32 v97, v102, v102
	v_mul_f32_e32 v117, v105, v105
	v_mul_f32_e32 v118, v107, v107
	v_add_f32_e32 v96, v96, v97
	v_mul_f32_e32 v97, v109, v109
	v_mul_f32_e32 v98, v111, v111
	v_fmac_f32_e32 v117, v104, v104
	v_fmac_f32_e32 v118, v106, v106
	v_fmac_f32_e32 v97, v108, v108
	v_fmac_f32_e32 v98, v110, v110
	v_add_f32_e32 v117, v117, v118
	v_add_f32_e32 v97, v97, v98
	v_add_f32_e32 v116, v116, v117
	v_add_f32_e32 v96, v96, v97
	v_add_f32_e32 v96, v116, v96
	v_mov_b32_e32 v97, v96
	s_nop 1
	v_permlane16_swap_b32_e32 v97, v96
	v_cvt_pk_bf16_f32 v98, v100, v101
	v_cvt_pk_bf16_f32 v99, v102, v103
	v_cvt_pk_bf16_f32 v100, v108, v109
	v_cvt_pk_bf16_f32 v101, v110, v111
	s_waitcnt lgkmcnt(0)
	v_add_f32_e32 v96, v96, v97
	v_mov_b32_e32 v97, v96
	s_nop 1
	v_permlane32_swap_b32_e32 v97, v96
	v_lshl_add_u64 v[102:103], v[114:115], 0, s[14:15]
	global_store_dwordx4 v[102:103], v[98:101], off sc1
	s_nop 1
	s_and_saveexec_b64 s[40:41], s[2:3]
	s_cbranch_execz .LBB0_893
	v_lshlrev_b64 v[98:99], 6, v[112:113]
	v_lshl_add_u64 v[98:99], s[38:39], 0, v[98:99]
	s_waitcnt lgkmcnt(0)
	v_add_f32_e32 v96, v96, v97
	global_store_dword v[98:99], v96, off sc1
.LBB0_893:
	s_or_b64 exec, exec, s[40:41]
	v_or_b32_e32 v96, 32, v138
	s_waitcnt lgkmcnt(0)
	v_ashrrev_i32_e32 v97, 31, v96
	v_mul_f32_e32 v100, v81, v81
	v_lshlrev_b64 v[98:99], 11, v[96:97]
	v_fmac_f32_e32 v100, v80, v80
	v_mul_f32_e32 v101, v83, v83
	v_cvt_pk_bf16_f32 v80, v80, v81
	v_cvt_pk_bf16_f32 v81, v82, v83
	v_lshl_add_u64 v[98:99], v[136:137], 0, v[98:99]
	v_fmac_f32_e32 v101, v82, v82
	v_cvt_pk_bf16_f32 v82, v88, v89
	v_cvt_pk_bf16_f32 v83, v90, v91
	v_add_f32_e32 v100, v100, v101
	global_store_dwordx4 v[98:99], v[80:83], off sc1
	s_nop 1
	v_mul_f32_e32 v80, v85, v85
	v_mul_f32_e32 v81, v87, v87
	v_fmac_f32_e32 v80, v84, v84
	v_fmac_f32_e32 v81, v86, v86
	v_mul_f32_e32 v101, v89, v89
	v_mul_f32_e32 v102, v91, v91
	v_add_f32_e32 v80, v80, v81
	v_mul_f32_e32 v81, v93, v93
	v_mul_f32_e32 v82, v95, v95
	v_fmac_f32_e32 v101, v88, v88
	v_fmac_f32_e32 v102, v90, v90
	v_fmac_f32_e32 v81, v92, v92
	v_fmac_f32_e32 v82, v94, v94
	v_add_f32_e32 v101, v101, v102
	v_add_f32_e32 v81, v81, v82
	v_add_f32_e32 v100, v100, v101
	v_add_f32_e32 v80, v80, v81
	v_add_f32_e32 v80, v100, v80
	v_mov_b32_e32 v81, v80
	s_nop 1
	v_permlane16_swap_b32_e32 v81, v80
	v_cvt_pk_bf16_f32 v82, v84, v85
	v_cvt_pk_bf16_f32 v83, v86, v87
	v_cvt_pk_bf16_f32 v84, v92, v93
	v_cvt_pk_bf16_f32 v85, v94, v95
	s_waitcnt lgkmcnt(0)
	v_add_f32_e32 v80, v80, v81
	v_mov_b32_e32 v81, v80
	s_nop 1
	v_permlane32_swap_b32_e32 v81, v80
	v_lshl_add_u64 v[86:87], v[98:99], 0, s[14:15]
	global_store_dwordx4 v[86:87], v[82:85], off sc1
	s_nop 1
	s_and_saveexec_b64 s[40:41], s[2:3]
	s_cbranch_execz .LBB0_895
	v_lshlrev_b64 v[82:83], 6, v[96:97]
	v_lshl_add_u64 v[82:83], s[38:39], 0, v[82:83]
	s_waitcnt lgkmcnt(0)
	v_add_f32_e32 v80, v80, v81
	global_store_dword v[82:83], v80, off sc1
; __device__ __forceinline__ void store16_wt(void* p, wt_u32x4 v) { asm volatile("global_store_dwordx4 %0, %1, off sc1\n\ts_nop 1" :: "v"(p), "v"(v) : "memory"); }
; __device__ __forceinline__ float lane_get(float v, int src_lane) { return __builtin_bit_cast(float, __builtin_amdgcn_ds_bpermute(src_lane << 2, __builtin_bit_cast(int, v))); }
; __device__ __forceinline__ unsigned cvt_pk_bf16(float lo, float hi) { unsigned r; asm volatile("v_cvt_pk_bf16_f32 %0, %1, %2" : "=v"(r) : "v"(lo), "v"(hi)); return r; }
;     __device__ __forceinline__ void operator()(const f32x4 (&acc)[2][2][4][2], const Unit& u, int wr, int wc, int fr, int fq, int ui) const {
;     ...
;         const int row0 = u.pm * BM + wr * 64 + fr, col0 = u.pn * BM + wc * 32 + 8 * fq, lane = fq * 16 + fr;
; #pragma unroll
;         for (int ai = 0; ai < 2; ++ai)
; #pragma unroll
;             for (int m = 0; m < 4; ++m) { const int row = row0 + ai * HALF + m * 16; bf16_t* rowb = XB + (size_t)row * ldc + col0; float ss = 0.f;
; #pragma unroll
;                 for (int bj = 0; bj < 2; ++bj) { const f32x4 x0 = acc[ai][bj][m][0], x1 = acc[ai][bj][m][1];
;                     ss += ((x0[0] * x0[0] + x0[1] * x0[1]) + (x0[2] * x0[2] + x0[3] * x0[3])) + ((x1[0] * x1[0] + x1[1] * x1[1]) + (x1[2] * x1[2] + x1[3] * x1[3]));
;                     u32x4 w; w.x = cvt_pk_bf16(x0[0], x0[1]); w.y = cvt_pk_bf16(x0[2], x0[3]); w.z = cvt_pk_bf16(x1[0], x1[1]); w.w = cvt_pk_bf16(x1[2], x1[3]); store16_wt(rowb + bj * HALF, w); }
;                 ss += lane_get(ss, lane ^ 16); ss += lane_get(ss, lane ^ 32);
;                 if (fq == 0) __hip_atomic_store((unsigned*)stats + (size_t)row * 16 + u.pn * 4 + wc, __float_as_uint(ss), __ATOMIC_RELAXED, __HIP_MEMORY_SCOPE_AGENT); }
.LBB0_895:
	s_or_b64 exec, exec, s[40:41]
	v_or_b32_e32 v80, 48, v138
	s_waitcnt lgkmcnt(0)
	v_ashrrev_i32_e32 v81, 31, v80
	v_mul_f32_e32 v84, v65, v65
	v_lshlrev_b64 v[82:83], 11, v[80:81]
	v_fmac_f32_e32 v84, v64, v64
	v_mul_f32_e32 v85, v67, v67
	v_cvt_pk_bf16_f32 v64, v64, v65
	v_cvt_pk_bf16_f32 v65, v66, v67
	v_lshl_add_u64 v[82:83], v[136:137], 0, v[82:83]
	v_fmac_f32_e32 v85, v66, v66
	v_cvt_pk_bf16_f32 v66, v72, v73
	v_cvt_pk_bf16_f32 v67, v74, v75
	v_add_f32_e32 v84, v84, v85
	global_store_dwordx4 v[82:83], v[64:67], off sc1
	s_nop 1
	v_mul_f32_e32 v64, v69, v69
	v_mul_f32_e32 v65, v71, v71
	v_fmac_f32_e32 v64, v68, v68
	v_fmac_f32_e32 v65, v70, v70
	v_mul_f32_e32 v85, v73, v73
	v_mul_f32_e32 v86, v75, v75
	v_add_f32_e32 v64, v64, v65
	v_mul_f32_e32 v65, v77, v77
	v_mul_f32_e32 v66, v79, v79
	v_fmac_f32_e32 v85, v72, v72
	v_fmac_f32_e32 v86, v74, v74
	v_fmac_f32_e32 v65, v76, v76
	v_fmac_f32_e32 v66, v78, v78
	v_add_f32_e32 v85, v85, v86
	v_add_f32_e32 v65, v65, v66
	v_add_f32_e32 v84, v84, v85
	v_add_f32_e32 v64, v64, v65
	v_add_f32_e32 v64, v84, v64
	v_mov_b32_e32 v65, v64
	s_nop 1
	v_permlane16_swap_b32_e32 v65, v64
	v_cvt_pk_bf16_f32 v66, v68, v69
	v_cvt_pk_bf16_f32 v67, v70, v71
	v_cvt_pk_bf16_f32 v68, v76, v77
	v_cvt_pk_bf16_f32 v69, v78, v79
	s_waitcnt lgkmcnt(0)
	v_add_f32_e32 v64, v64, v65
	v_mov_b32_e32 v65, v64
	s_nop 1
	v_permlane32_swap_b32_e32 v65, v64
	v_lshl_add_u64 v[70:71], v[82:83], 0, s[14:15]
	global_store_dwordx4 v[70:71], v[66:69], off sc1
	s_nop 1
	s_and_saveexec_b64 s[40:41], s[2:3]
	s_cbranch_execz .LBB0_897
	v_lshlrev_b64 v[66:67], 6, v[80:81]
	v_lshl_add_u64 v[66:67], s[38:39], 0, v[66:67]
	s_waitcnt lgkmcnt(0)
	v_add_f32_e32 v64, v64, v65
	global_store_dword v[66:67], v64, off sc1
.LBB0_897:
	s_or_b64 exec, exec, s[40:41]
	v_add_u32_e32 v64, 0x80, v138
	s_waitcnt lgkmcnt(0)
	v_ashrrev_i32_e32 v65, 31, v64
	v_mul_f32_e32 v68, v49, v49
	v_lshlrev_b64 v[66:67], 11, v[64:65]
	v_fmac_f32_e32 v68, v48, v48
	v_mul_f32_e32 v69, v51, v51
	v_cvt_pk_bf16_f32 v48, v48, v49
	v_cvt_pk_bf16_f32 v49, v50, v51
	v_lshl_add_u64 v[66:67], v[136:137], 0, v[66:67]
	v_fmac_f32_e32 v69, v50, v50
	v_cvt_pk_bf16_f32 v50, v56, v57
	v_cvt_pk_bf16_f32 v51, v58, v59
	v_add_f32_e32 v68, v68, v69
	global_store_dwordx4 v[66:67], v[48:51], off sc1
	s_nop 1
	v_mul_f32_e32 v48, v53, v53
	v_mul_f32_e32 v49, v55, v55
	v_fmac_f32_e32 v48, v52, v52
	v_fmac_f32_e32 v49, v54, v54
	v_mul_f32_e32 v69, v57, v57
	v_mul_f32_e32 v70, v59, v59
	v_add_f32_e32 v48, v48, v49
	v_mul_f32_e32 v49, v61, v61
	v_mul_f32_e32 v50, v63, v63
	v_fmac_f32_e32 v69, v56, v56
	v_fmac_f32_e32 v70, v58, v58
	v_fmac_f32_e32 v49, v60, v60
	v_fmac_f32_e32 v50, v62, v62
	v_add_f32_e32 v69, v69, v70
	v_add_f32_e32 v49, v49, v50
	v_add_f32_e32 v68, v68, v69
	v_add_f32_e32 v48, v48, v49
	v_add_f32_e32 v48, v68, v48
	v_mov_b32_e32 v49, v48
	s_nop 1
	v_permlane16_swap_b32_e32 v49, v48
	v_cvt_pk_bf16_f32 v50, v52, v53
	v_cvt_pk_bf16_f32 v51, v54, v55
	v_cvt_pk_bf16_f32 v52, v60, v61
	v_cvt_pk_bf16_f32 v53, v62, v63
	s_waitcnt lgkmcnt(0)
	v_add_f32_e32 v48, v48, v49
	v_mov_b32_e32 v49, v48
	s_nop 1
	v_permlane32_swap_b32_e32 v49, v48
	v_lshl_add_u64 v[54:55], v[66:67], 0, s[14:15]
	global_store_dwordx4 v[54:55], v[50:53], off sc1
	s_nop 1
	s_and_saveexec_b64 s[40:41], s[2:3]
	s_cbranch_execz .LBB0_899
	v_lshlrev_b64 v[50:51], 6, v[64:65]
	v_lshl_add_u64 v[50:51], s[38:39], 0, v[50:51]
	s_waitcnt lgkmcnt(0)
	v_add_f32_e32 v48, v48, v49
	global_store_dword v[50:51], v48, off sc1
; __device__ __forceinline__ void store16_wt(void* p, wt_u32x4 v) { asm volatile("global_store_dwordx4 %0, %1, off sc1\n\ts_nop 1" :: "v"(p), "v"(v) : "memory"); }
; __device__ __forceinline__ float lane_get(float v, int src_lane) { return __builtin_bit_cast(float, __builtin_amdgcn_ds_bpermute(src_lane << 2, __builtin_bit_cast(int, v))); }
; __device__ __forceinline__ unsigned cvt_pk_bf16(float lo, float hi) { unsigned r; asm volatile("v_cvt_pk_bf16_f32 %0, %1, %2" : "=v"(r) : "v"(lo), "v"(hi)); return r; }
;     __device__ __forceinline__ void operator()(const f32x4 (&acc)[2][2][4][2], const Unit& u, int wr, int wc, int fr, int fq, int ui) const {
;     ...
;         const int row0 = u.pm * BM + wr * 64 + fr, col0 = u.pn * BM + wc * 32 + 8 * fq, lane = fq * 16 + fr;
; #pragma unroll
;         for (int ai = 0; ai < 2; ++ai)
; #pragma unroll
;             for (int m = 0; m < 4; ++m) { const int row = row0 + ai * HALF + m * 16; bf16_t* rowb = XB + (size_t)row * ldc + col0; float ss = 0.f;
; #pragma unroll
;                 for (int bj = 0; bj < 2; ++bj) { const f32x4 x0 = acc[ai][bj][m][0], x1 = acc[ai][bj][m][1];
;                     ss += ((x0[0] * x0[0] + x0[1] * x0[1]) + (x0[2] * x0[2] + x0[3] * x0[3])) + ((x1[0] * x1[0] + x1[1] * x1[1]) + (x1[2] * x1[2] + x1[3] * x1[3]));
;                     u32x4 w; w.x = cvt_pk_bf16(x0[0], x0[1]); w.y = cvt_pk_bf16(x0[2], x0[3]); w.z = cvt_pk_bf16(x1[0], x1[1]); w.w = cvt_pk_bf16(x1[2], x1[3]); store16_wt(rowb + bj * HALF, w); }
;                 ss += lane_get(ss, lane ^ 16); ss += lane_get(ss, lane ^ 32);
;                 if (fq == 0) __hip_atomic_store((unsigned*)stats + (size_t)row * 16 + u.pn * 4 + wc, __float_as_uint(ss), __ATOMIC_RELAXED, __HIP_MEMORY_SCOPE_AGENT); }
.LBB0_899:
	s_or_b64 exec, exec, s[40:41]
	v_add_u32_e32 v48, 0x90, v138
	s_waitcnt lgkmcnt(0)
	v_ashrrev_i32_e32 v49, 31, v48
	v_mul_f32_e32 v52, v17, v17
	v_lshlrev_b64 v[50:51], 11, v[48:49]
	v_fmac_f32_e32 v52, v16, v16
	v_mul_f32_e32 v53, v19, v19
	v_cvt_pk_bf16_f32 v16, v16, v17
	v_cvt_pk_bf16_f32 v17, v18, v19
	v_lshl_add_u64 v[50:51], v[136:137], 0, v[50:51]
	v_fmac_f32_e32 v53, v18, v18
	v_cvt_pk_bf16_f32 v18, v24, v25
	v_cvt_pk_bf16_f32 v19, v26, v27
	v_add_f32_e32 v52, v52, v53
	global_store_dwordx4 v[50:51], v[16:19], off sc1
	s_nop 1
	v_mul_f32_e32 v16, v21, v21
	v_mul_f32_e32 v17, v23, v23
	v_fmac_f32_e32 v16, v20, v20
	v_fmac_f32_e32 v17, v22, v22
	v_mul_f32_e32 v53, v25, v25
	v_mul_f32_e32 v54, v27, v27
	v_add_f32_e32 v16, v16, v17
	v_mul_f32_e32 v17, v29, v29
	v_mul_f32_e32 v18, v31, v31
	v_fmac_f32_e32 v53, v24, v24
	v_fmac_f32_e32 v54, v26, v26
	v_fmac_f32_e32 v17, v28, v28
	v_fmac_f32_e32 v18, v30, v30
	v_add_f32_e32 v53, v53, v54
	v_add_f32_e32 v17, v17, v18
	v_add_f32_e32 v52, v52, v53
	v_add_f32_e32 v16, v16, v17
	v_add_f32_e32 v16, v52, v16
	v_mov_b32_e32 v17, v16
	s_nop 1
	v_permlane16_swap_b32_e32 v17, v16
	v_cvt_pk_bf16_f32 v18, v20, v21
	v_cvt_pk_bf16_f32 v19, v22, v23
	v_cvt_pk_bf16_f32 v20, v28, v29
	v_cvt_pk_bf16_f32 v21, v30, v31
	s_waitcnt lgkmcnt(0)
	v_add_f32_e32 v16, v16, v17
	v_mov_b32_e32 v17, v16
	s_nop 1
	v_permlane32_swap_b32_e32 v17, v16
	v_lshl_add_u64 v[22:23], v[50:51], 0, s[14:15]
	global_store_dwordx4 v[22:23], v[18:21], off sc1
	s_nop 1
	s_and_saveexec_b64 s[40:41], s[2:3]
	s_cbranch_execz .LBB0_901
	v_lshlrev_b64 v[18:19], 6, v[48:49]
	v_lshl_add_u64 v[18:19], s[38:39], 0, v[18:19]
	s_waitcnt lgkmcnt(0)
	v_add_f32_e32 v16, v16, v17
	global_store_dword v[18:19], v16, off sc1
.LBB0_901:
	s_or_b64 exec, exec, s[40:41]
	v_add_u32_e32 v16, 0xa0, v138
	s_waitcnt lgkmcnt(0)
	v_ashrrev_i32_e32 v17, 31, v16
	v_lshlrev_b64 v[18:19], 11, v[16:17]
	v_lshl_add_u64 v[24:25], v[136:137], 0, v[18:19]
	v_mul_f32_e32 v18, v33, v33
	v_mul_f32_e32 v19, v35, v35
	v_fmac_f32_e32 v18, v32, v32
	v_fmac_f32_e32 v19, v34, v34
	v_add_f32_e32 v18, v18, v19
	v_mul_f32_e32 v19, v41, v41
	v_mul_f32_e32 v20, v43, v43
	v_fmac_f32_e32 v19, v40, v40
	v_fmac_f32_e32 v20, v42, v42
	v_add_f32_e32 v19, v19, v20
	v_add_f32_e32 v22, v18, v19
	v_cvt_pk_bf16_f32 v18, v32, v33
	v_cvt_pk_bf16_f32 v19, v34, v35
	v_cvt_pk_bf16_f32 v20, v40, v41
	v_cvt_pk_bf16_f32 v21, v42, v43
	s_nop 0
	global_store_dwordx4 v[24:25], v[18:21], off sc1
	s_nop 1
	v_mul_f32_e32 v18, v37, v37
	v_mul_f32_e32 v19, v39, v39
	v_fmac_f32_e32 v18, v36, v36
	v_fmac_f32_e32 v19, v38, v38
	v_add_f32_e32 v18, v18, v19
	v_mul_f32_e32 v19, v45, v45
	v_mul_f32_e32 v20, v47, v47
	v_fmac_f32_e32 v19, v44, v44
	v_fmac_f32_e32 v20, v46, v46
	v_add_f32_e32 v19, v19, v20
	v_add_f32_e32 v18, v18, v19
	v_add_f32_e32 v18, v22, v18
	v_mov_b32_e32 v19, v18
	s_nop 1
	v_permlane16_swap_b32_e32 v19, v18
	v_cvt_pk_bf16_f32 v20, v36, v37
	v_cvt_pk_bf16_f32 v21, v38, v39
	v_cvt_pk_bf16_f32 v22, v44, v45
	v_cvt_pk_bf16_f32 v23, v46, v47
	s_waitcnt lgkmcnt(0)
	v_add_f32_e32 v18, v18, v19
	v_mov_b32_e32 v19, v18
	s_nop 1
	v_permlane32_swap_b32_e32 v19, v18
	v_lshl_add_u64 v[24:25], v[24:25], 0, s[14:15]
	global_store_dwordx4 v[24:25], v[20:23], off sc1
	s_nop 1
	s_and_saveexec_b64 s[40:41], s[2:3]
	s_cbranch_execz .LBB0_903
	v_lshlrev_b64 v[16:17], 6, v[16:17]
	v_lshl_add_u64 v[16:17], s[38:39], 0, v[16:17]
	s_waitcnt lgkmcnt(0)
	v_add_f32_e32 v18, v18, v19
	global_store_dword v[16:17], v18, off sc1
.LBB0_903:
	s_or_b64 exec, exec, s[40:41]
	v_add_u32_e32 v16, 0xb0, v138
	v_ashrrev_i32_e32 v17, 31, v16
	v_mul_f32_e32 v20, v1, v1
	s_waitcnt lgkmcnt(0)
	v_lshlrev_b64 v[18:19], 11, v[16:17]
	v_fmac_f32_e32 v20, v0, v0
	v_mul_f32_e32 v21, v3, v3
	v_cvt_pk_bf16_f32 v0, v0, v1
	v_cvt_pk_bf16_f32 v1, v2, v3
	v_lshl_add_u64 v[18:19], v[136:137], 0, v[18:19]
	v_fmac_f32_e32 v21, v2, v2
	v_cvt_pk_bf16_f32 v2, v8, v9
	v_cvt_pk_bf16_f32 v3, v10, v11
	v_add_f32_e32 v20, v20, v21
	global_store_dwordx4 v[18:19], v[0:3], off sc1
	s_nop 1
	v_mul_f32_e32 v0, v5, v5
	v_mul_f32_e32 v1, v7, v7
	v_fmac_f32_e32 v0, v4, v4
	v_fmac_f32_e32 v1, v6, v6
	v_mul_f32_e32 v21, v9, v9
	v_mul_f32_e32 v22, v11, v11
	v_add_f32_e32 v0, v0, v1
	v_mul_f32_e32 v1, v13, v13
	v_mul_f32_e32 v2, v15, v15
	v_fmac_f32_e32 v21, v8, v8
	v_fmac_f32_e32 v22, v10, v10
	v_fmac_f32_e32 v1, v12, v12
	v_fmac_f32_e32 v2, v14, v14
	v_add_f32_e32 v21, v21, v22
	v_add_f32_e32 v1, v1, v2
	v_add_f32_e32 v20, v20, v21
	v_add_f32_e32 v0, v0, v1
	v_add_f32_e32 v0, v20, v0
	v_mov_b32_e32 v1, v0
	s_nop 1
	v_permlane16_swap_b32_e32 v1, v0
	v_cvt_pk_bf16_f32 v2, v4, v5
	v_cvt_pk_bf16_f32 v3, v6, v7
	v_cvt_pk_bf16_f32 v4, v12, v13
	v_cvt_pk_bf16_f32 v5, v14, v15
	s_waitcnt lgkmcnt(0)
	v_add_f32_e32 v0, v0, v1
	v_mov_b32_e32 v1, v0
	s_nop 1
	v_permlane32_swap_b32_e32 v1, v0
	v_lshl_add_u64 v[6:7], v[18:19], 0, s[14:15]
	global_store_dwordx4 v[6:7], v[2:5], off sc1
	s_nop 1
	s_and_saveexec_b64 s[40:41], s[2:3]
	s_cbranch_execz .LBB0_905
	v_lshlrev_b64 v[2:3], 6, v[16:17]
	v_lshl_add_u64 v[2:3], s[38:39], 0, v[2:3]
	s_waitcnt lgkmcnt(0)
	v_add_f32_e32 v0, v0, v1
	global_store_dword v[2:3], v0, off sc1
